# P7 tail re-tiled to 64x64 sub-tiles per workgroup (half the operand bytes), pipelined loads; plus early L1 invalidate in grid barrier and GLA item remap
# speedup vs baseline: 1.0391x; 1.0137x over previous
.LBB0_1488:
	s_ashr_i32 s23, s69, 4
	s_add_i32 s23, s23, s33
	s_ashr_i32 s24, s23, 31
	s_lshr_b32 s24, s24, 29
	s_add_i32 s24, s23, s24
	s_ashr_i32 s25, s24, 3
	s_and_b32 s24, s24, -8
	s_sub_i32 s23, s23, s24
	s_cmp_lt_i32 s23, 0
	s_cselect_b32 s24, 35, 34
	s_mul_i32 s23, s23, s24
	s_add_i32 s23, s23, s25
	s_ashr_i32 s24, s23, 31
	s_lshr_b32 s24, s24, 27
	s_add_i32 s24, s23, s24
	s_ashr_i32 s25, s24, 5
	s_andn2_b32 s24, s24, 31
	s_lshl_b32 s25, s25, 3
	s_sub_i32 s24, s23, s24
	s_sub_i32 s23, 0x44, s25
	s_min_i32 s23, s23, 8
	s_abs_i32 s28, s23
	v_cvt_f32_u32_e32 v0, s28
	s_sub_i32 s29, 0, s28
	s_abs_i32 s26, s24
	s_xor_b32 s27, s24, s23
	v_rcp_iflag_f32_e32 v0, v0
	s_ashr_i32 s27, s27, 31
	v_mul_f32_e32 v0, 0x4f7ffffe, v0
	v_cvt_u32_f32_e32 v0, v0
	s_nop 0
	v_readfirstlane_b32 s30, v0
	s_mul_i32 s29, s29, s30
	s_mul_hi_u32 s29, s30, s29
	s_add_i32 s30, s30, s29
	s_mul_hi_u32 s29, s26, s30
	s_mul_i32 s30, s29, s28
	s_sub_i32 s26, s26, s30
	s_add_i32 s31, s29, 1
	s_sub_i32 s30, s26, s28
	s_cmp_ge_u32 s26, s28
	s_cselect_b32 s29, s31, s29
	s_cselect_b32 s26, s30, s26
	s_add_i32 s30, s29, 1
	s_cmp_ge_u32 s26, s28
	s_cselect_b32 s26, s30, s29
	s_xor_b32 s26, s26, s27
	s_sub_i32 s26, s26, s27
	s_mul_i32 s27, s26, s23
	s_lshl_b32 s23, s26, 8
	s_and_b32 s64, s1, 0x30
	s_lshl_b32 s64, s64, 2
	s_or_b32 s23, s23, s64
	s_sub_i32 s24, s24, s27
	v_or_b32_e32 v0, s23, v179
	s_add_i32 s26, s25, s24
	v_mad_i64_i32 v[44:45], s[24:25], v0, s2, v[42:43]
	s_and_b32 s28, s1, 0xc0
	s_lshl_b32 s24, s26, 8
	s_or_b32 s24, s24, s28
	v_or_b32_e32 v0, s24, v179
	v_mad_i64_i32 v[46:47], s[26:27], v0, s2, v[40:41]
	s_add_i32 s69, s69, s94
	s_add_i32 s1, s1, s72
	s_cmp_lt_i32 s69, s0
	v_lshl_add_u64 v[0:1], v[46:47], 0, s[34:35]
	v_lshl_add_u64 v[6:7], v[44:45], 0, s[34:35]
	v_lshl_add_u64 v[2:3], v[46:47], 0, s[36:37]
	v_lshl_add_u64 v[8:9], v[44:45], 0, s[36:37]
	v_lshl_add_u64 v[4:5], v[46:47], 0, s[38:39]
	v_lshl_add_u64 v[10:11], v[44:45], 0, s[38:39]
	global_load_dwordx4 v[48:51], v[46:47], off
	global_load_dwordx4 v[52:55], v[46:47], off offset:64
	global_load_dwordx4 v[56:59], v[0:1], off
	global_load_dwordx4 v[60:63], v[0:1], off offset:64
	global_load_dwordx4 v[64:67], v[2:3], off
	global_load_dwordx4 v[68:71], v[2:3], off offset:64
	global_load_dwordx4 v[72:75], v[4:5], off
	global_load_dwordx4 v[76:79], v[4:5], off offset:64
	global_load_dwordx4 v[80:83], v[44:45], off
	global_load_dwordx4 v[84:87], v[44:45], off offset:64
	global_load_dwordx4 v[88:91], v[6:7], off
	global_load_dwordx4 v[92:95], v[6:7], off offset:64
	global_load_dwordx4 v[96:99], v[8:9], off
	global_load_dwordx4 v[100:103], v[8:9], off offset:64
	global_load_dwordx4 v[104:107], v[10:11], off
	global_load_dwordx4 v[108:111], v[10:11], off offset:64
	global_load_dwordx4 v[112:115], v[46:47], off offset:128
	global_load_dwordx4 v[116:119], v[46:47], off offset:192
	global_load_dwordx4 v[120:123], v[0:1], off offset:128
	global_load_dwordx4 v[124:127], v[0:1], off offset:192
	global_load_dwordx4 v[128:131], v[2:3], off offset:128
	global_load_dwordx4 v[132:135], v[2:3], off offset:192
	global_load_dwordx4 v[136:139], v[4:5], off offset:128
	global_load_dwordx4 v[140:143], v[4:5], off offset:192
	global_load_dwordx4 v[144:147], v[44:45], off offset:128
	global_load_dwordx4 v[148:151], v[44:45], off offset:192
	global_load_dwordx4 v[152:155], v[6:7], off offset:128
	global_load_dwordx4 v[156:159], v[6:7], off offset:192
	global_load_dwordx4 v[160:163], v[8:9], off offset:128
	global_load_dwordx4 v[164:167], v[8:9], off offset:192
	global_load_dwordx4 v[168:171], v[10:11], off offset:128
	global_load_dwordx4 v[172:175], v[10:11], off offset:192
	s_waitcnt vmcnt(16)
	v_mfma_f32_16x16x32_bf16 v[32:35], v[48:51], v[80:83], 0
	v_mfma_f32_16x16x32_bf16 v[36:39], v[48:51], v[88:91], 0
	v_mfma_f32_16x16x32_bf16 v[180:183], v[48:51], v[96:99], 0
	v_mfma_f32_16x16x32_bf16 v[184:187], v[48:51], v[104:107], 0
	v_mfma_f32_16x16x32_bf16 v[188:191], v[56:59], v[80:83], 0
	v_mfma_f32_16x16x32_bf16 v[192:195], v[56:59], v[88:91], 0
	v_mfma_f32_16x16x32_bf16 v[196:199], v[56:59], v[96:99], 0
	v_mfma_f32_16x16x32_bf16 v[200:203], v[56:59], v[104:107], 0
	v_mfma_f32_16x16x32_bf16 v[204:207], v[64:67], v[80:83], 0
	v_mfma_f32_16x16x32_bf16 v[222:225], v[64:67], v[88:91], 0
	v_mfma_f32_16x16x32_bf16 v[226:229], v[64:67], v[96:99], 0
	v_mfma_f32_16x16x32_bf16 v[230:233], v[64:67], v[104:107], 0
	v_mfma_f32_16x16x32_bf16 v[234:237], v[72:75], v[80:83], 0
	v_mfma_f32_16x16x32_bf16 v[238:241], v[72:75], v[88:91], 0
	v_mfma_f32_16x16x32_bf16 v[242:245], v[72:75], v[96:99], 0
	v_mfma_f32_16x16x32_bf16 v[252:255], v[72:75], v[104:107], 0
	v_mfma_f32_16x16x32_bf16 v[32:35], v[52:55], v[84:87], v[32:35]
	v_mfma_f32_16x16x32_bf16 v[36:39], v[52:55], v[92:95], v[36:39]
	v_mfma_f32_16x16x32_bf16 v[180:183], v[52:55], v[100:103], v[180:183]
	v_mfma_f32_16x16x32_bf16 v[184:187], v[52:55], v[108:111], v[184:187]
	v_mfma_f32_16x16x32_bf16 v[188:191], v[60:63], v[84:87], v[188:191]
	v_mfma_f32_16x16x32_bf16 v[192:195], v[60:63], v[92:95], v[192:195]
	v_mfma_f32_16x16x32_bf16 v[196:199], v[60:63], v[100:103], v[196:199]
	v_mfma_f32_16x16x32_bf16 v[200:203], v[60:63], v[108:111], v[200:203]
	v_mfma_f32_16x16x32_bf16 v[204:207], v[68:71], v[84:87], v[204:207]
	v_mfma_f32_16x16x32_bf16 v[222:225], v[68:71], v[92:95], v[222:225]
	v_mfma_f32_16x16x32_bf16 v[226:229], v[68:71], v[100:103], v[226:229]
	v_mfma_f32_16x16x32_bf16 v[230:233], v[68:71], v[108:111], v[230:233]
	v_mfma_f32_16x16x32_bf16 v[234:237], v[76:79], v[84:87], v[234:237]
	v_mfma_f32_16x16x32_bf16 v[238:241], v[76:79], v[92:95], v[238:241]
	v_mfma_f32_16x16x32_bf16 v[242:245], v[76:79], v[100:103], v[242:245]
	v_mfma_f32_16x16x32_bf16 v[252:255], v[76:79], v[108:111], v[252:255]
	global_load_dwordx4 v[48:51], v[46:47], off offset:256
	global_load_dwordx4 v[52:55], v[46:47], off offset:320
	global_load_dwordx4 v[56:59], v[0:1], off offset:256
	global_load_dwordx4 v[60:63], v[0:1], off offset:320
	global_load_dwordx4 v[64:67], v[2:3], off offset:256
	global_load_dwordx4 v[68:71], v[2:3], off offset:320
	global_load_dwordx4 v[72:75], v[4:5], off offset:256
	global_load_dwordx4 v[76:79], v[4:5], off offset:320
	global_load_dwordx4 v[80:83], v[44:45], off offset:256
	global_load_dwordx4 v[84:87], v[44:45], off offset:320
	global_load_dwordx4 v[88:91], v[6:7], off offset:256
	global_load_dwordx4 v[92:95], v[6:7], off offset:320
	global_load_dwordx4 v[96:99], v[8:9], off offset:256
	global_load_dwordx4 v[100:103], v[8:9], off offset:320
	global_load_dwordx4 v[104:107], v[10:11], off offset:256
	global_load_dwordx4 v[108:111], v[10:11], off offset:320
	s_waitcnt vmcnt(16)
	v_mfma_f32_16x16x32_bf16 v[32:35], v[112:115], v[144:147], v[32:35]
	v_mfma_f32_16x16x32_bf16 v[36:39], v[112:115], v[152:155], v[36:39]
	v_mfma_f32_16x16x32_bf16 v[180:183], v[112:115], v[160:163], v[180:183]
	v_mfma_f32_16x16x32_bf16 v[184:187], v[112:115], v[168:171], v[184:187]
	v_mfma_f32_16x16x32_bf16 v[188:191], v[120:123], v[144:147], v[188:191]
	v_mfma_f32_16x16x32_bf16 v[192:195], v[120:123], v[152:155], v[192:195]
	v_mfma_f32_16x16x32_bf16 v[196:199], v[120:123], v[160:163], v[196:199]
	v_mfma_f32_16x16x32_bf16 v[200:203], v[120:123], v[168:171], v[200:203]
	v_mfma_f32_16x16x32_bf16 v[204:207], v[128:131], v[144:147], v[204:207]
	v_mfma_f32_16x16x32_bf16 v[222:225], v[128:131], v[152:155], v[222:225]
	v_mfma_f32_16x16x32_bf16 v[226:229], v[128:131], v[160:163], v[226:229]
	v_mfma_f32_16x16x32_bf16 v[230:233], v[128:131], v[168:171], v[230:233]
	v_mfma_f32_16x16x32_bf16 v[234:237], v[136:139], v[144:147], v[234:237]
	v_mfma_f32_16x16x32_bf16 v[238:241], v[136:139], v[152:155], v[238:241]
	v_mfma_f32_16x16x32_bf16 v[242:245], v[136:139], v[160:163], v[242:245]
	v_mfma_f32_16x16x32_bf16 v[252:255], v[136:139], v[168:171], v[252:255]
	v_mfma_f32_16x16x32_bf16 v[32:35], v[116:119], v[148:151], v[32:35]
	v_mfma_f32_16x16x32_bf16 v[36:39], v[116:119], v[156:159], v[36:39]
	v_mfma_f32_16x16x32_bf16 v[180:183], v[116:119], v[164:167], v[180:183]
	v_mfma_f32_16x16x32_bf16 v[184:187], v[116:119], v[172:175], v[184:187]
	v_mfma_f32_16x16x32_bf16 v[188:191], v[124:127], v[148:151], v[188:191]
	v_mfma_f32_16x16x32_bf16 v[192:195], v[124:127], v[156:159], v[192:195]
	v_mfma_f32_16x16x32_bf16 v[196:199], v[124:127], v[164:167], v[196:199]
	v_mfma_f32_16x16x32_bf16 v[200:203], v[124:127], v[172:175], v[200:203]
	v_mfma_f32_16x16x32_bf16 v[204:207], v[132:135], v[148:151], v[204:207]
	v_mfma_f32_16x16x32_bf16 v[222:225], v[132:135], v[156:159], v[222:225]
	v_mfma_f32_16x16x32_bf16 v[226:229], v[132:135], v[164:167], v[226:229]
	v_mfma_f32_16x16x32_bf16 v[230:233], v[132:135], v[172:175], v[230:233]
	v_mfma_f32_16x16x32_bf16 v[234:237], v[140:143], v[148:151], v[234:237]
	v_mfma_f32_16x16x32_bf16 v[238:241], v[140:143], v[156:159], v[238:241]
	v_mfma_f32_16x16x32_bf16 v[242:245], v[140:143], v[164:167], v[242:245]
	v_mfma_f32_16x16x32_bf16 v[252:255], v[140:143], v[172:175], v[252:255]
	global_load_dwordx4 v[112:115], v[46:47], off offset:384
	global_load_dwordx4 v[116:119], v[46:47], off offset:448
	global_load_dwordx4 v[120:123], v[0:1], off offset:384
	global_load_dwordx4 v[124:127], v[0:1], off offset:448
	global_load_dwordx4 v[128:131], v[2:3], off offset:384
	global_load_dwordx4 v[132:135], v[2:3], off offset:448
	global_load_dwordx4 v[136:139], v[4:5], off offset:384
	global_load_dwordx4 v[140:143], v[4:5], off offset:448
	global_load_dwordx4 v[144:147], v[44:45], off offset:384
	global_load_dwordx4 v[148:151], v[44:45], off offset:448
	global_load_dwordx4 v[152:155], v[6:7], off offset:384
	global_load_dwordx4 v[156:159], v[6:7], off offset:448
	global_load_dwordx4 v[160:163], v[8:9], off offset:384
	global_load_dwordx4 v[164:167], v[8:9], off offset:448
	global_load_dwordx4 v[168:171], v[10:11], off offset:384
	global_load_dwordx4 v[172:175], v[10:11], off offset:448
	s_waitcnt vmcnt(16)
	v_mfma_f32_16x16x32_bf16 v[32:35], v[48:51], v[80:83], v[32:35]
	v_mfma_f32_16x16x32_bf16 v[36:39], v[48:51], v[88:91], v[36:39]
	v_mfma_f32_16x16x32_bf16 v[180:183], v[48:51], v[96:99], v[180:183]
	v_mfma_f32_16x16x32_bf16 v[184:187], v[48:51], v[104:107], v[184:187]
	v_mfma_f32_16x16x32_bf16 v[188:191], v[56:59], v[80:83], v[188:191]
	v_mfma_f32_16x16x32_bf16 v[192:195], v[56:59], v[88:91], v[192:195]
	v_mfma_f32_16x16x32_bf16 v[196:199], v[56:59], v[96:99], v[196:199]
	v_mfma_f32_16x16x32_bf16 v[200:203], v[56:59], v[104:107], v[200:203]
	v_mfma_f32_16x16x32_bf16 v[204:207], v[64:67], v[80:83], v[204:207]
	v_mfma_f32_16x16x32_bf16 v[222:225], v[64:67], v[88:91], v[222:225]
	v_mfma_f32_16x16x32_bf16 v[226:229], v[64:67], v[96:99], v[226:229]
	v_mfma_f32_16x16x32_bf16 v[230:233], v[64:67], v[104:107], v[230:233]
	v_mfma_f32_16x16x32_bf16 v[234:237], v[72:75], v[80:83], v[234:237]
	v_mfma_f32_16x16x32_bf16 v[238:241], v[72:75], v[88:91], v[238:241]
	v_mfma_f32_16x16x32_bf16 v[242:245], v[72:75], v[96:99], v[242:245]
	v_mfma_f32_16x16x32_bf16 v[252:255], v[72:75], v[104:107], v[252:255]
	v_mfma_f32_16x16x32_bf16 v[32:35], v[52:55], v[84:87], v[32:35]
	v_mfma_f32_16x16x32_bf16 v[36:39], v[52:55], v[92:95], v[36:39]
	v_mfma_f32_16x16x32_bf16 v[180:183], v[52:55], v[100:103], v[180:183]
	v_mfma_f32_16x16x32_bf16 v[184:187], v[52:55], v[108:111], v[184:187]
	v_mfma_f32_16x16x32_bf16 v[188:191], v[60:63], v[84:87], v[188:191]
	v_mfma_f32_16x16x32_bf16 v[192:195], v[60:63], v[92:95], v[192:195]
	v_mfma_f32_16x16x32_bf16 v[196:199], v[60:63], v[100:103], v[196:199]
	v_mfma_f32_16x16x32_bf16 v[200:203], v[60:63], v[108:111], v[200:203]
	v_mfma_f32_16x16x32_bf16 v[204:207], v[68:71], v[84:87], v[204:207]
	v_mfma_f32_16x16x32_bf16 v[222:225], v[68:71], v[92:95], v[222:225]
	v_mfma_f32_16x16x32_bf16 v[226:229], v[68:71], v[100:103], v[226:229]
	v_mfma_f32_16x16x32_bf16 v[230:233], v[68:71], v[108:111], v[230:233]
	v_mfma_f32_16x16x32_bf16 v[234:237], v[76:79], v[84:87], v[234:237]
	v_mfma_f32_16x16x32_bf16 v[238:241], v[76:79], v[92:95], v[238:241]
	v_mfma_f32_16x16x32_bf16 v[242:245], v[76:79], v[100:103], v[242:245]
	v_mfma_f32_16x16x32_bf16 v[252:255], v[76:79], v[108:111], v[252:255]
	global_load_dwordx4 v[48:51], v[46:47], off offset:512
	global_load_dwordx4 v[52:55], v[46:47], off offset:576
	global_load_dwordx4 v[56:59], v[0:1], off offset:512
	global_load_dwordx4 v[60:63], v[0:1], off offset:576
	global_load_dwordx4 v[64:67], v[2:3], off offset:512
	global_load_dwordx4 v[68:71], v[2:3], off offset:576
	global_load_dwordx4 v[72:75], v[4:5], off offset:512
	global_load_dwordx4 v[76:79], v[4:5], off offset:576
	global_load_dwordx4 v[80:83], v[44:45], off offset:512
	global_load_dwordx4 v[84:87], v[44:45], off offset:576
	global_load_dwordx4 v[88:91], v[6:7], off offset:512
	global_load_dwordx4 v[92:95], v[6:7], off offset:576
	global_load_dwordx4 v[96:99], v[8:9], off offset:512
	global_load_dwordx4 v[100:103], v[8:9], off offset:576
	global_load_dwordx4 v[104:107], v[10:11], off offset:512
	global_load_dwordx4 v[108:111], v[10:11], off offset:576
	s_waitcnt vmcnt(16)
	v_mfma_f32_16x16x32_bf16 v[32:35], v[112:115], v[144:147], v[32:35]
	v_mfma_f32_16x16x32_bf16 v[36:39], v[112:115], v[152:155], v[36:39]
	v_mfma_f32_16x16x32_bf16 v[180:183], v[112:115], v[160:163], v[180:183]
	v_mfma_f32_16x16x32_bf16 v[184:187], v[112:115], v[168:171], v[184:187]
	v_mfma_f32_16x16x32_bf16 v[188:191], v[120:123], v[144:147], v[188:191]
	v_mfma_f32_16x16x32_bf16 v[192:195], v[120:123], v[152:155], v[192:195]
	v_mfma_f32_16x16x32_bf16 v[196:199], v[120:123], v[160:163], v[196:199]
	v_mfma_f32_16x16x32_bf16 v[200:203], v[120:123], v[168:171], v[200:203]
	v_mfma_f32_16x16x32_bf16 v[204:207], v[128:131], v[144:147], v[204:207]
	v_mfma_f32_16x16x32_bf16 v[222:225], v[128:131], v[152:155], v[222:225]
	v_mfma_f32_16x16x32_bf16 v[226:229], v[128:131], v[160:163], v[226:229]
	v_mfma_f32_16x16x32_bf16 v[230:233], v[128:131], v[168:171], v[230:233]
	v_mfma_f32_16x16x32_bf16 v[234:237], v[136:139], v[144:147], v[234:237]
	v_mfma_f32_16x16x32_bf16 v[238:241], v[136:139], v[152:155], v[238:241]
	v_mfma_f32_16x16x32_bf16 v[242:245], v[136:139], v[160:163], v[242:245]
	v_mfma_f32_16x16x32_bf16 v[252:255], v[136:139], v[168:171], v[252:255]
	v_mfma_f32_16x16x32_bf16 v[32:35], v[116:119], v[148:151], v[32:35]
	v_mfma_f32_16x16x32_bf16 v[36:39], v[116:119], v[156:159], v[36:39]
	v_mfma_f32_16x16x32_bf16 v[180:183], v[116:119], v[164:167], v[180:183]
	v_mfma_f32_16x16x32_bf16 v[184:187], v[116:119], v[172:175], v[184:187]
	v_mfma_f32_16x16x32_bf16 v[188:191], v[124:127], v[148:151], v[188:191]
	v_mfma_f32_16x16x32_bf16 v[192:195], v[124:127], v[156:159], v[192:195]
	v_mfma_f32_16x16x32_bf16 v[196:199], v[124:127], v[164:167], v[196:199]
	v_mfma_f32_16x16x32_bf16 v[200:203], v[124:127], v[172:175], v[200:203]
	v_mfma_f32_16x16x32_bf16 v[204:207], v[132:135], v[148:151], v[204:207]
	v_mfma_f32_16x16x32_bf16 v[222:225], v[132:135], v[156:159], v[222:225]
	v_mfma_f32_16x16x32_bf16 v[226:229], v[132:135], v[164:167], v[226:229]
	v_mfma_f32_16x16x32_bf16 v[230:233], v[132:135], v[172:175], v[230:233]
	v_mfma_f32_16x16x32_bf16 v[234:237], v[140:143], v[148:151], v[234:237]
	v_mfma_f32_16x16x32_bf16 v[238:241], v[140:143], v[156:159], v[238:241]
	v_mfma_f32_16x16x32_bf16 v[242:245], v[140:143], v[164:167], v[242:245]
	v_mfma_f32_16x16x32_bf16 v[252:255], v[140:143], v[172:175], v[252:255]
	global_load_dwordx4 v[112:115], v[46:47], off offset:640
	global_load_dwordx4 v[120:123], v[0:1], off offset:640
	global_load_dwordx4 v[128:131], v[2:3], off offset:640
	global_load_dwordx4 v[136:139], v[4:5], off offset:640
	global_load_dwordx4 v[144:147], v[44:45], off offset:640
	global_load_dwordx4 v[152:155], v[6:7], off offset:640
	global_load_dwordx4 v[160:163], v[8:9], off offset:640
	global_load_dwordx4 v[168:171], v[10:11], off offset:640
	s_waitcnt vmcnt(8)
	v_mfma_f32_16x16x32_bf16 v[32:35], v[48:51], v[80:83], v[32:35]
	v_mfma_f32_16x16x32_bf16 v[36:39], v[48:51], v[88:91], v[36:39]
	v_mfma_f32_16x16x32_bf16 v[180:183], v[48:51], v[96:99], v[180:183]
	v_mfma_f32_16x16x32_bf16 v[184:187], v[48:51], v[104:107], v[184:187]
	v_mfma_f32_16x16x32_bf16 v[188:191], v[56:59], v[80:83], v[188:191]
	v_mfma_f32_16x16x32_bf16 v[192:195], v[56:59], v[88:91], v[192:195]
	v_mfma_f32_16x16x32_bf16 v[196:199], v[56:59], v[96:99], v[196:199]
	v_mfma_f32_16x16x32_bf16 v[200:203], v[56:59], v[104:107], v[200:203]
	v_mfma_f32_16x16x32_bf16 v[204:207], v[64:67], v[80:83], v[204:207]
	v_mfma_f32_16x16x32_bf16 v[222:225], v[64:67], v[88:91], v[222:225]
	v_mfma_f32_16x16x32_bf16 v[226:229], v[64:67], v[96:99], v[226:229]
	v_mfma_f32_16x16x32_bf16 v[230:233], v[64:67], v[104:107], v[230:233]
	v_mfma_f32_16x16x32_bf16 v[234:237], v[72:75], v[80:83], v[234:237]
	v_mfma_f32_16x16x32_bf16 v[238:241], v[72:75], v[88:91], v[238:241]
	v_mfma_f32_16x16x32_bf16 v[242:245], v[72:75], v[96:99], v[242:245]
	v_mfma_f32_16x16x32_bf16 v[252:255], v[72:75], v[104:107], v[252:255]
	v_mfma_f32_16x16x32_bf16 v[32:35], v[52:55], v[84:87], v[32:35]
	v_mfma_f32_16x16x32_bf16 v[36:39], v[52:55], v[92:95], v[36:39]
	v_mfma_f32_16x16x32_bf16 v[180:183], v[52:55], v[100:103], v[180:183]
	v_mfma_f32_16x16x32_bf16 v[184:187], v[52:55], v[108:111], v[184:187]
	v_mfma_f32_16x16x32_bf16 v[188:191], v[60:63], v[84:87], v[188:191]
	v_mfma_f32_16x16x32_bf16 v[192:195], v[60:63], v[92:95], v[192:195]
	v_mfma_f32_16x16x32_bf16 v[196:199], v[60:63], v[100:103], v[196:199]
	v_mfma_f32_16x16x32_bf16 v[200:203], v[60:63], v[108:111], v[200:203]
	v_mfma_f32_16x16x32_bf16 v[204:207], v[68:71], v[84:87], v[204:207]
	v_mfma_f32_16x16x32_bf16 v[222:225], v[68:71], v[92:95], v[222:225]
	v_mfma_f32_16x16x32_bf16 v[226:229], v[68:71], v[100:103], v[226:229]
	v_mfma_f32_16x16x32_bf16 v[230:233], v[68:71], v[108:111], v[230:233]
	v_mfma_f32_16x16x32_bf16 v[234:237], v[76:79], v[84:87], v[234:237]
	v_mfma_f32_16x16x32_bf16 v[238:241], v[76:79], v[92:95], v[238:241]
	v_mfma_f32_16x16x32_bf16 v[242:245], v[76:79], v[100:103], v[242:245]
	v_mfma_f32_16x16x32_bf16 v[252:255], v[76:79], v[108:111], v[252:255]
	s_waitcnt vmcnt(0)
	v_mfma_f32_16x16x32_bf16 v[32:35], v[112:115], v[144:147], v[32:35]
	v_mfma_f32_16x16x32_bf16 v[36:39], v[112:115], v[152:155], v[36:39]
	v_mfma_f32_16x16x32_bf16 v[180:183], v[112:115], v[160:163], v[180:183]
	v_mfma_f32_16x16x32_bf16 v[184:187], v[112:115], v[168:171], v[184:187]
	v_mfma_f32_16x16x32_bf16 v[188:191], v[120:123], v[144:147], v[188:191]
	v_mfma_f32_16x16x32_bf16 v[192:195], v[120:123], v[152:155], v[192:195]
	v_mfma_f32_16x16x32_bf16 v[196:199], v[120:123], v[160:163], v[196:199]
	v_mfma_f32_16x16x32_bf16 v[200:203], v[120:123], v[168:171], v[200:203]
	v_mfma_f32_16x16x32_bf16 v[204:207], v[128:131], v[144:147], v[204:207]
	v_mfma_f32_16x16x32_bf16 v[222:225], v[128:131], v[152:155], v[222:225]
	v_mfma_f32_16x16x32_bf16 v[226:229], v[128:131], v[160:163], v[226:229]
	v_mfma_f32_16x16x32_bf16 v[230:233], v[128:131], v[168:171], v[230:233]
	v_mfma_f32_16x16x32_bf16 v[234:237], v[136:139], v[144:147], v[234:237]
	v_mfma_f32_16x16x32_bf16 v[238:241], v[136:139], v[152:155], v[238:241]
	v_mfma_f32_16x16x32_bf16 v[242:245], v[136:139], v[160:163], v[242:245]
	v_mfma_f32_16x16x32_bf16 v[252:255], v[136:139], v[168:171], v[252:255]
	v_and_b32_e32 v78, 0x2f, v211
	v_add_u32_e32 v78, s23, v78
	v_ashrrev_i32_e32 v79, 31, v78
	v_lshlrev_b64 v[82:83], 1, v[78:79]
	v_lshrrev_b32_e32 v44, 2, v211
	v_and_b32_e32 v44, 0x30, v44
	v_or3_b32 v44, v44, v210, s24
	v_ashrrev_i32_e32 v45, 31, v44
	v_or_b32_e32 v84, 1, v44
	v_ashrrev_i32_e32 v85, 31, v84
	s_barrier
	v_or_b32_e32 v86, 2, v44
	v_or_b32_e32 v88, 3, v44
	v_lshlrev_b64 v[44:45], 11, v[44:45]
	v_ashrrev_i32_e32 v87, 31, v86
	v_ashrrev_i32_e32 v89, 31, v88
	v_lshl_add_u64 v[44:45], s[16:17], 0, v[44:45]
	v_lshlrev_b64 v[70:71], 11, v[84:85]
	v_lshlrev_b64 v[72:73], 11, v[86:87]
	v_lshlrev_b64 v[84:85], 11, v[88:89]
	v_lshl_add_u64 v[86:87], v[44:45], 0, v[82:83]
	v_lshl_add_u64 v[44:45], s[16:17], 0, v[70:71]
	v_lshl_add_u64 v[70:71], s[16:17], 0, v[72:73]
	v_lshl_add_u64 v[72:73], s[16:17], 0, v[84:85]
	v_lshl_add_u64 v[84:85], v[44:45], 0, v[82:83]
	v_lshl_add_u64 v[70:71], v[70:71], 0, v[82:83]
	v_lshl_add_u64 v[72:73], v[72:73], 0, v[82:83]
	ds_write_b128 v220, v[32:35]
	ds_write_b128 v220, v[36:39] offset:1024
	ds_write_b128 v220, v[180:183] offset:2048
	ds_write_b128 v220, v[184:187] offset:3072
	ds_write_b128 v220, v[188:191] offset:4096
	ds_write_b128 v220, v[192:195] offset:5120
	ds_write_b128 v220, v[196:199] offset:6144
	ds_write_b128 v220, v[200:203] offset:7168
	ds_write_b128 v220, v[204:207] offset:8192
	ds_write_b128 v220, v[222:225] offset:9216
	ds_write_b128 v220, v[226:229] offset:10240
	ds_write_b128 v220, v[230:233] offset:11264
	ds_write_b128 v220, v[234:237] offset:12288
	ds_write_b128 v220, v[238:241] offset:13312
	ds_write_b128 v220, v[242:245] offset:14336
	ds_write_b128 v220, v[252:255] offset:15360
	s_waitcnt lgkmcnt(0)
	s_barrier
	global_load_ushort v68, v[86:87], off
	global_load_ushort v69, v[86:87], off offset:32
	global_load_ushort v74, v[84:85], off
	global_load_ushort v75, v[84:85], off offset:32
	global_load_ushort v76, v[70:71], off
	global_load_ushort v77, v[70:71], off offset:32
	global_load_ushort v78, v[72:73], off
	global_load_ushort v79, v[72:73], off offset:32
	ds_read_b128 v[0:3], v177
	ds_read_b128 v[4:7], v177 offset:1024
	ds_read_b128 v[8:11], v177 offset:16384
	ds_read_b128 v[12:15], v177 offset:17408
	ds_read_b128 v[16:19], v177 offset:32768
	ds_read_b128 v[20:23], v177 offset:33792
	ds_read_b128 v[24:27], v177 offset:49152
	ds_read_b128 v[28:31], v177 offset:50176
	ds_read_b128 v[32:35], v212
	ds_read_b128 v[36:39], v213
	ds_read_b128 v[44:47], v214
	ds_read_b128 v[48:51], v215
	ds_read_b128 v[52:55], v216
	ds_read_b128 v[56:59], v217
	ds_read_b128 v[60:63], v218
	ds_read_b128 v[64:67], v219
	s_waitcnt lgkmcnt(14)
	v_pk_add_f32 v[0:1], v[0:1], 0 op_sel_hi:[1,0]
	v_pk_add_f32 v[2:3], v[2:3], 0 op_sel_hi:[1,0]
	v_pk_add_f32 v[6:7], v[6:7], 0 op_sel_hi:[1,0]
	v_pk_add_f32 v[4:5], v[4:5], 0 op_sel_hi:[1,0]
	s_waitcnt lgkmcnt(13)
	v_pk_add_f32 v[0:1], v[0:1], v[8:9]
	v_pk_add_f32 v[2:3], v[2:3], v[10:11]
	s_waitcnt lgkmcnt(12)
	v_pk_add_f32 v[6:7], v[6:7], v[14:15]
	v_pk_add_f32 v[4:5], v[4:5], v[12:13]
	s_waitcnt lgkmcnt(11)
	v_pk_add_f32 v[0:1], v[0:1], v[16:17]
	v_pk_add_f32 v[2:3], v[2:3], v[18:19]
	s_waitcnt lgkmcnt(10)
	v_pk_add_f32 v[6:7], v[6:7], v[22:23]
	v_pk_add_f32 v[4:5], v[4:5], v[20:21]
	s_waitcnt lgkmcnt(9)
	v_pk_add_f32 v[0:1], v[0:1], v[24:25]
	v_pk_add_f32 v[2:3], v[2:3], v[26:27]
	s_waitcnt lgkmcnt(8)
	v_pk_add_f32 v[6:7], v[6:7], v[30:31]
	v_pk_add_f32 v[4:5], v[4:5], v[28:29]
	s_waitcnt lgkmcnt(7)
	v_pk_add_f32 v[0:1], v[0:1], v[32:33]
	v_pk_add_f32 v[2:3], v[2:3], v[34:35]
	s_waitcnt lgkmcnt(6)
	v_pk_add_f32 v[6:7], v[6:7], v[38:39]
	v_pk_add_f32 v[4:5], v[4:5], v[36:37]
	s_waitcnt lgkmcnt(5)
	v_pk_add_f32 v[0:1], v[0:1], v[44:45]
	v_pk_add_f32 v[2:3], v[2:3], v[46:47]
	s_waitcnt lgkmcnt(4)
	v_pk_add_f32 v[6:7], v[6:7], v[50:51]
	v_pk_add_f32 v[4:5], v[4:5], v[48:49]
	s_waitcnt lgkmcnt(3)
	v_pk_add_f32 v[0:1], v[0:1], v[52:53]
	v_pk_add_f32 v[2:3], v[2:3], v[54:55]
	s_waitcnt lgkmcnt(2)
	v_pk_add_f32 v[6:7], v[6:7], v[58:59]
	v_pk_add_f32 v[4:5], v[4:5], v[56:57]
	s_waitcnt lgkmcnt(1)
	v_pk_add_f32 v[0:1], v[0:1], v[60:61]
	v_pk_add_f32 v[2:3], v[2:3], v[62:63]
	s_waitcnt lgkmcnt(0)
	v_pk_add_f32 v[6:7], v[6:7], v[66:67]
	v_pk_add_f32 v[4:5], v[4:5], v[64:65]
	s_waitcnt vmcnt(7)
	v_lshlrev_b32_e32 v8, 16, v68
	s_waitcnt vmcnt(6)
	v_lshlrev_b32_e32 v9, 16, v69
	s_waitcnt vmcnt(5)
	v_lshlrev_b32_e32 v10, 16, v74
	s_waitcnt vmcnt(4)
	v_lshlrev_b32_e32 v11, 16, v75
	s_waitcnt vmcnt(3)
	v_lshlrev_b32_e32 v12, 16, v76
	s_waitcnt vmcnt(2)
	v_lshlrev_b32_e32 v13, 16, v77
	s_waitcnt vmcnt(1)
	v_lshlrev_b32_e32 v14, 16, v78
	s_waitcnt vmcnt(0)
	v_lshlrev_b32_e32 v15, 16, v79
	v_add_f32_e32 v0, v0, v8
	v_add_f32_e32 v4, v4, v9
	v_add_f32_e32 v1, v1, v10
	v_add_f32_e32 v5, v5, v11
	v_add_f32_e32 v2, v2, v12
	v_add_f32_e32 v6, v6, v13
	v_add_f32_e32 v3, v3, v14
	v_add_f32_e32 v7, v7, v15
	v_bfe_u32 v8, v0, 16, 1
	v_bfe_u32 v9, v4, 16, 1
	v_bfe_u32 v10, v1, 16, 1
	v_bfe_u32 v11, v5, 16, 1
	v_bfe_u32 v12, v2, 16, 1
	v_bfe_u32 v13, v6, 16, 1
	v_bfe_u32 v14, v3, 16, 1
	v_bfe_u32 v15, v7, 16, 1
	v_add3_u32 v0, v0, v8, s22
	v_add3_u32 v4, v4, v9, s22
	v_add3_u32 v1, v1, v10, s22
	v_add3_u32 v5, v5, v11, s22
	v_add3_u32 v2, v2, v12, s22
	v_add3_u32 v6, v6, v13, s22
	v_add3_u32 v3, v3, v14, s22
	v_add3_u32 v7, v7, v15, s22
	global_store_short_d16_hi v[86:87], v0, off
	global_store_short_d16_hi v[86:87], v4, off offset:32
	global_store_short_d16_hi v[84:85], v1, off
	global_store_short_d16_hi v[84:85], v5, off offset:32
	global_store_short_d16_hi v[70:71], v2, off
	global_store_short_d16_hi v[70:71], v6, off offset:32
	global_store_short_d16_hi v[72:73], v3, off
	global_store_short_d16_hi v[72:73], v7, off offset:32
	s_cbranch_scc1 .LBB0_1488
